# waitcnt placement: MLP-up epilogue's wait for the 1/rms LDS table reads moved down to the first consumer; two dead address instructions removed
# baseline (speedup 1.0000x reference)
; __device__ __forceinline__ unsigned cvt_pk_bf16(float lo, float hi) { const f32x2c_t v = {lo, hi}; const bf16x2c_t b = __builtin_convertvector(v, bf16x2c_t); return __builtin_bit_cast(unsigned, b); }
;     __device__ __forceinline__ void operator()(const f32x4 (&acc)[2][2][4][2], const Unit& u, int wr, int wc, int fr, int fq) const {
;     ...
;             for (int m = 0; m < 4; ++m) { const size_t row = (size_t)(row0 + ai * HALF + m * 16);
;                 const f32x4* sp = (const f32x4*)(SS + row * 32) + 2 * fq; float s;
;                 { const f32x4 t0 = sp[0], t1 = sp[1]; s = ((t0[0] + t0[1]) + (t0[2] + t0[3])) + ((t1[0] + t1[1]) + (t1[2] + t1[3])); }
;                 s += __shfl_xor(s, 16); s += __shfl_xor(s, 32);
;                 const float rstd = 1.0f / sqrtf(s * (1.0f / DM) + NORM_EPS);
; #pragma unroll
;                 for (int bj = 0; bj < 2; ++bj) { f32x4 v0 = acc[ai][bj][m][0] * rstd, v1 = acc[ai][bj][m][1] * rstd;
; #pragma unroll
;                     for (int e = 0; e < 4; ++e) { const float a = fmaxf(v0[e], 0.f), b = fmaxf(v1[e], 0.f); v0[e] = a * a; v1[e] = b * b; }
;                     u32x4 w; w.x = cvt_pk_bf16(v0[0], v0[1]); w.y = cvt_pk_bf16(v0[2], v0[3]); w.z = cvt_pk_bf16(v1[0], v1[1]); w.w = cvt_pk_bf16(v1[2], v1[3]);
;                     *(u32x4*)(H + row * DFF + col0 + bj * HALF) = w; } }
.LBB0_79:
	v_lshlrev_b32_e32 v220, 2, v1
	v_add_u32_e32 v220, 0x22c00, v220
	ds_read_b32 v204, v220 offset:0
	ds_read_b32 v206, v220 offset:64
	ds_read_b32 v208, v220 offset:128
	ds_read_b32 v210, v220 offset:192
	ds_read_b32 v212, v220 offset:512
	ds_read_b32 v214, v220 offset:576
	ds_read_b32 v216, v220 offset:640
	ds_read_b32 v218, v220 offset:704
	v_xor_b32_e32 v159, 16, v192
	v_add_u32_e32 v163, 64, v193
	v_cmp_lt_i32_e32 vcc, v159, v163
	v_lshl_add_u32 v158, s34, 8, v1
	v_lshl_or_b32 v172, s28, 8, v160
	v_cndmask_b32_e32 v159, v192, v159, vcc
	v_lshlrev_b32_e32 v162, 2, v159
	v_xor_b32_e32 v159, 32, v192
	v_cmp_lt_i32_e32 vcc, v159, v163
	v_ashrrev_i32_e32 v173, 31, v172
	s_nop 0
	v_cndmask_b32_e32 v159, v192, v159, vcc
	v_lshlrev_b32_e32 v163, 2, v159
	v_ashrrev_i32_e32 v159, 31, v158
	v_lshlrev_b64 v[164:165], 7, v[158:159]
	s_waitcnt lgkmcnt(0)
	v_pk_mul_f32 v[128:129], v[128:129], v[204:205] op_sel_hi:[1,0]
	v_pk_mul_f32 v[126:127], v[126:127], v[204:205] op_sel_hi:[1,0]
	v_pk_mul_f32 v[122:123], v[122:123], v[204:205] op_sel_hi:[1,0]
	v_pk_mul_f32 v[124:125], v[124:125], v[204:205] op_sel_hi:[1,0]
	v_max_f32_e32 v126, 0, v126
	v_max_f32_e32 v122, 0, v122
	v_max_f32_e32 v127, 0, v127
	v_max_f32_e32 v123, 0, v123
	v_max_f32_e32 v128, 0, v128
	v_max_f32_e32 v129, 0, v129
	v_lshlrev_b64 v[166:167], 14, v[158:159]
	v_pk_mul_f32 v[126:127], v[126:127], v[126:127]
	v_pk_mul_f32 v[122:123], v[122:123], v[122:123]
	v_max_f32_e32 v124, 0, v124
	v_max_f32_e32 v125, 0, v125
	v_pk_mul_f32 v[128:129], v[128:129], v[128:129]
	v_pk_mul_f32 v[168:169], v[124:125], v[124:125]
	v_cvt_pk_bf16_f32 v124, v126, v127
	v_cvt_pk_bf16_f32 v125, v128, v129
	v_cvt_pk_bf16_f32 v126, v122, v123
	v_lshl_add_u64 v[128:129], s[92:93], 0, v[166:167]
	v_lshlrev_b64 v[122:123], 1, v[172:173]
	v_pk_mul_f32 v[114:115], v[114:115], v[204:205] op_sel_hi:[1,0]
	v_cvt_pk_bf16_f32 v127, v168, v169
	v_lshl_add_u64 v[128:129], v[128:129], 0, v[122:123]
	v_pk_mul_f32 v[120:121], v[120:121], v[204:205] op_sel_hi:[1,0]
	v_pk_mul_f32 v[118:119], v[118:119], v[204:205] op_sel_hi:[1,0]
	v_pk_mul_f32 v[116:117], v[116:117], v[204:205] op_sel_hi:[1,0]
	v_max_f32_e32 v114, 0, v114
	v_max_f32_e32 v115, 0, v115
	global_store_dwordx4 v[128:129], v[124:127], off
	v_max_f32_e32 v118, 0, v118
	v_max_f32_e32 v119, 0, v119
	v_pk_mul_f32 v[124:125], v[114:115], v[114:115]
	v_max_f32_e32 v114, 0, v120
	v_max_f32_e32 v116, 0, v116
	v_max_f32_e32 v115, 0, v121
	v_max_f32_e32 v117, 0, v117
	v_pk_mul_f32 v[118:119], v[118:119], v[118:119]
	v_pk_mul_f32 v[120:121], v[114:115], v[114:115]
	v_pk_mul_f32 v[126:127], v[116:117], v[116:117]
	v_cvt_pk_bf16_f32 v114, v118, v119
	v_cvt_pk_bf16_f32 v115, v120, v121
	v_cvt_pk_bf16_f32 v116, v124, v125
	v_cvt_pk_bf16_f32 v117, v126, v127
	global_store_dwordx4 v[128:129], v[114:117], off offset:256
	s_nop 1
	v_or_b32_e32 v114, 16, v158
	v_ashrrev_i32_e32 v115, 31, v114
	v_lshlrev_b64 v[116:117], 7, v[114:115]
	v_lshlrev_b64 v[114:115], 14, v[114:115]
	v_pk_mul_f32 v[110:111], v[110:111], v[206:207] op_sel_hi:[1,0]
	v_pk_mul_f32 v[106:107], v[106:107], v[206:207] op_sel_hi:[1,0]
	v_pk_mul_f32 v[112:113], v[112:113], v[206:207] op_sel_hi:[1,0]
	v_pk_mul_f32 v[108:109], v[108:109], v[206:207] op_sel_hi:[1,0]
	v_max_f32_e32 v110, 0, v110
	v_max_f32_e32 v106, 0, v106
	v_max_f32_e32 v111, 0, v111
	v_max_f32_e32 v107, 0, v107
	v_pk_mul_f32 v[110:111], v[110:111], v[110:111]
	v_pk_mul_f32 v[118:119], v[106:107], v[106:107]
	v_max_f32_e32 v106, 0, v112
	v_max_f32_e32 v108, 0, v108
	v_max_f32_e32 v107, 0, v113
	v_max_f32_e32 v109, 0, v109
	v_pk_mul_f32 v[112:113], v[106:107], v[106:107]
	v_pk_mul_f32 v[120:121], v[108:109], v[108:109]
	v_cvt_pk_bf16_f32 v106, v110, v111
	v_lshl_add_u64 v[110:111], s[92:93], 0, v[114:115]
	v_pk_mul_f32 v[98:99], v[98:99], v[206:207] op_sel_hi:[1,0]
	v_cvt_pk_bf16_f32 v107, v112, v113
	v_cvt_pk_bf16_f32 v108, v118, v119
	v_cvt_pk_bf16_f32 v109, v120, v121
	v_lshl_add_u64 v[110:111], v[110:111], 0, v[122:123]
	v_pk_mul_f32 v[104:105], v[104:105], v[206:207] op_sel_hi:[1,0]
	v_pk_mul_f32 v[102:103], v[102:103], v[206:207] op_sel_hi:[1,0]
	v_pk_mul_f32 v[100:101], v[100:101], v[206:207] op_sel_hi:[1,0]
	v_max_f32_e32 v98, 0, v98
	v_max_f32_e32 v99, 0, v99
	global_store_dwordx4 v[110:111], v[106:109], off
	v_max_f32_e32 v102, 0, v102
	v_max_f32_e32 v103, 0, v103
	v_pk_mul_f32 v[106:107], v[98:99], v[98:99]
	v_max_f32_e32 v98, 0, v104
	v_max_f32_e32 v100, 0, v100
	v_max_f32_e32 v99, 0, v105
	v_max_f32_e32 v101, 0, v101
	v_pk_mul_f32 v[102:103], v[102:103], v[102:103]
	v_pk_mul_f32 v[104:105], v[98:99], v[98:99]
	v_pk_mul_f32 v[108:109], v[100:101], v[100:101]
	v_cvt_pk_bf16_f32 v98, v102, v103
	v_cvt_pk_bf16_f32 v99, v104, v105
	v_cvt_pk_bf16_f32 v100, v106, v107
	v_cvt_pk_bf16_f32 v101, v108, v109
	global_store_dwordx4 v[110:111], v[98:101], off offset:256
	s_nop 1
	v_or_b32_e32 v98, 32, v158
	v_ashrrev_i32_e32 v99, 31, v98
	v_lshlrev_b64 v[100:101], 7, v[98:99]
	v_lshl_add_u64 v[100:101], v[152:153], 0, v[100:101]
	v_lshlrev_b64 v[98:99], 14, v[98:99]
	v_pk_mul_f32 v[94:95], v[94:95], v[208:209] op_sel_hi:[1,0]
	v_pk_mul_f32 v[90:91], v[90:91], v[208:209] op_sel_hi:[1,0]
	v_pk_mul_f32 v[96:97], v[96:97], v[208:209] op_sel_hi:[1,0]
	v_pk_mul_f32 v[92:93], v[92:93], v[208:209] op_sel_hi:[1,0]
	v_max_f32_e32 v94, 0, v94
	v_max_f32_e32 v90, 0, v90
	v_max_f32_e32 v95, 0, v95
	v_max_f32_e32 v91, 0, v91
	v_pk_mul_f32 v[94:95], v[94:95], v[94:95]
	v_pk_mul_f32 v[102:103], v[90:91], v[90:91]
	v_max_f32_e32 v90, 0, v96
	v_max_f32_e32 v92, 0, v92
	v_max_f32_e32 v91, 0, v97
	v_max_f32_e32 v93, 0, v93
	v_pk_mul_f32 v[96:97], v[90:91], v[90:91]
; __device__ __forceinline__ unsigned cvt_pk_bf16(float lo, float hi) { const f32x2c_t v = {lo, hi}; const bf16x2c_t b = __builtin_convertvector(v, bf16x2c_t); return __builtin_bit_cast(unsigned, b); }
;     __device__ __forceinline__ void operator()(const f32x4 (&acc)[2][2][4][2], const Unit& u, int wr, int wc, int fr, int fq) const {
;     ...
;             for (int m = 0; m < 4; ++m) { const size_t row = (size_t)(row0 + ai * HALF + m * 16);
;                 const f32x4* sp = (const f32x4*)(SS + row * 32) + 2 * fq; float s;
;                 { const f32x4 t0 = sp[0], t1 = sp[1]; s = ((t0[0] + t0[1]) + (t0[2] + t0[3])) + ((t1[0] + t1[1]) + (t1[2] + t1[3])); }
;                 s += __shfl_xor(s, 16); s += __shfl_xor(s, 32);
;                 const float rstd = 1.0f / sqrtf(s * (1.0f / DM) + NORM_EPS);
; #pragma unroll
;                 for (int bj = 0; bj < 2; ++bj) { f32x4 v0 = acc[ai][bj][m][0] * rstd, v1 = acc[ai][bj][m][1] * rstd;
; #pragma unroll
;                     for (int e = 0; e < 4; ++e) { const float a = fmaxf(v0[e], 0.f), b = fmaxf(v1[e], 0.f); v0[e] = a * a; v1[e] = b * b; }
;                     u32x4 w; w.x = cvt_pk_bf16(v0[0], v0[1]); w.y = cvt_pk_bf16(v0[2], v0[3]); w.z = cvt_pk_bf16(v1[0], v1[1]); w.w = cvt_pk_bf16(v1[2], v1[3]);
;                     *(u32x4*)(H + row * DFF + col0 + bj * HALF) = w; } }
	v_pk_mul_f32 v[104:105], v[92:93], v[92:93]
	v_cvt_pk_bf16_f32 v90, v94, v95
	v_lshl_add_u64 v[94:95], s[92:93], 0, v[98:99]
	v_pk_mul_f32 v[82:83], v[82:83], v[208:209] op_sel_hi:[1,0]
	v_cvt_pk_bf16_f32 v91, v96, v97
	v_cvt_pk_bf16_f32 v92, v102, v103
	v_cvt_pk_bf16_f32 v93, v104, v105
	v_lshl_add_u64 v[94:95], v[94:95], 0, v[122:123]
	v_pk_mul_f32 v[88:89], v[88:89], v[208:209] op_sel_hi:[1,0]
	v_pk_mul_f32 v[86:87], v[86:87], v[208:209] op_sel_hi:[1,0]
	v_pk_mul_f32 v[84:85], v[84:85], v[208:209] op_sel_hi:[1,0]
	v_max_f32_e32 v82, 0, v82
	v_max_f32_e32 v83, 0, v83
	global_store_dwordx4 v[94:95], v[90:93], off
	v_max_f32_e32 v86, 0, v86
	v_max_f32_e32 v87, 0, v87
	v_pk_mul_f32 v[90:91], v[82:83], v[82:83]
	v_max_f32_e32 v82, 0, v88
	v_max_f32_e32 v84, 0, v84
	v_max_f32_e32 v83, 0, v89
	v_max_f32_e32 v85, 0, v85
	v_pk_mul_f32 v[86:87], v[86:87], v[86:87]
	v_pk_mul_f32 v[88:89], v[82:83], v[82:83]
	v_pk_mul_f32 v[92:93], v[84:85], v[84:85]
	v_cvt_pk_bf16_f32 v82, v86, v87
	v_cvt_pk_bf16_f32 v83, v88, v89
	v_cvt_pk_bf16_f32 v84, v90, v91
	v_cvt_pk_bf16_f32 v85, v92, v93
	global_store_dwordx4 v[94:95], v[82:85], off offset:256
	s_nop 1
	v_or_b32_e32 v82, 48, v158
	v_ashrrev_i32_e32 v83, 31, v82
	v_lshlrev_b64 v[84:85], 7, v[82:83]
	v_lshl_add_u64 v[84:85], v[152:153], 0, v[84:85]
	v_lshlrev_b64 v[82:83], 14, v[82:83]
	v_pk_mul_f32 v[78:79], v[78:79], v[210:211] op_sel_hi:[1,0]
	v_pk_mul_f32 v[74:75], v[74:75], v[210:211] op_sel_hi:[1,0]
	v_pk_mul_f32 v[80:81], v[80:81], v[210:211] op_sel_hi:[1,0]
	v_pk_mul_f32 v[76:77], v[76:77], v[210:211] op_sel_hi:[1,0]
	v_max_f32_e32 v78, 0, v78
	v_max_f32_e32 v74, 0, v74
	v_max_f32_e32 v79, 0, v79
	v_max_f32_e32 v75, 0, v75
	v_pk_mul_f32 v[78:79], v[78:79], v[78:79]
	v_pk_mul_f32 v[86:87], v[74:75], v[74:75]
	v_max_f32_e32 v74, 0, v80
	v_max_f32_e32 v76, 0, v76
	v_max_f32_e32 v75, 0, v81
	v_max_f32_e32 v77, 0, v77
	v_pk_mul_f32 v[80:81], v[74:75], v[74:75]
	v_pk_mul_f32 v[88:89], v[76:77], v[76:77]
	v_cvt_pk_bf16_f32 v74, v78, v79
	v_lshl_add_u64 v[78:79], s[92:93], 0, v[82:83]
	v_pk_mul_f32 v[66:67], v[66:67], v[210:211] op_sel_hi:[1,0]
	v_cvt_pk_bf16_f32 v75, v80, v81
	v_cvt_pk_bf16_f32 v76, v86, v87
	v_cvt_pk_bf16_f32 v77, v88, v89
	v_lshl_add_u64 v[78:79], v[78:79], 0, v[122:123]
	v_pk_mul_f32 v[72:73], v[72:73], v[210:211] op_sel_hi:[1,0]
	v_pk_mul_f32 v[70:71], v[70:71], v[210:211] op_sel_hi:[1,0]
	v_pk_mul_f32 v[68:69], v[68:69], v[210:211] op_sel_hi:[1,0]
	v_max_f32_e32 v66, 0, v66
	v_max_f32_e32 v67, 0, v67
	global_store_dwordx4 v[78:79], v[74:77], off
	v_max_f32_e32 v70, 0, v70
	v_max_f32_e32 v71, 0, v71
	v_pk_mul_f32 v[74:75], v[66:67], v[66:67]
	v_max_f32_e32 v66, 0, v72
	v_max_f32_e32 v68, 0, v68
	v_max_f32_e32 v67, 0, v73
	v_max_f32_e32 v69, 0, v69
	v_pk_mul_f32 v[70:71], v[70:71], v[70:71]
	v_pk_mul_f32 v[72:73], v[66:67], v[66:67]
	v_pk_mul_f32 v[76:77], v[68:69], v[68:69]
	v_cvt_pk_bf16_f32 v66, v70, v71
	v_cvt_pk_bf16_f32 v67, v72, v73
	v_cvt_pk_bf16_f32 v68, v74, v75
	v_cvt_pk_bf16_f32 v69, v76, v77
	global_store_dwordx4 v[78:79], v[66:69], off offset:256
	s_nop 1
	v_add_u32_e32 v66, 0x80, v158
	v_ashrrev_i32_e32 v67, 31, v66
	v_lshlrev_b64 v[68:69], 7, v[66:67]
	v_lshl_add_u64 v[68:69], v[152:153], 0, v[68:69]
	v_lshlrev_b64 v[66:67], 14, v[66:67]
	v_pk_mul_f32 v[62:63], v[62:63], v[212:213] op_sel_hi:[1,0]
	v_pk_mul_f32 v[58:59], v[58:59], v[212:213] op_sel_hi:[1,0]
	v_pk_mul_f32 v[64:65], v[64:65], v[212:213] op_sel_hi:[1,0]
	v_pk_mul_f32 v[60:61], v[60:61], v[212:213] op_sel_hi:[1,0]
	v_max_f32_e32 v62, 0, v62
	v_max_f32_e32 v58, 0, v58
	v_max_f32_e32 v63, 0, v63
	v_max_f32_e32 v59, 0, v59
	v_pk_mul_f32 v[62:63], v[62:63], v[62:63]
	v_pk_mul_f32 v[70:71], v[58:59], v[58:59]
	v_max_f32_e32 v58, 0, v64
	v_max_f32_e32 v60, 0, v60
	v_max_f32_e32 v59, 0, v65
	v_max_f32_e32 v61, 0, v61
	v_pk_mul_f32 v[64:65], v[58:59], v[58:59]
	v_pk_mul_f32 v[72:73], v[60:61], v[60:61]
	v_cvt_pk_bf16_f32 v58, v62, v63
	v_lshl_add_u64 v[62:63], s[92:93], 0, v[66:67]
	v_pk_mul_f32 v[50:51], v[50:51], v[212:213] op_sel_hi:[1,0]
	v_cvt_pk_bf16_f32 v59, v64, v65
	v_cvt_pk_bf16_f32 v60, v70, v71
	v_cvt_pk_bf16_f32 v61, v72, v73
	v_lshl_add_u64 v[62:63], v[62:63], 0, v[122:123]
	v_pk_mul_f32 v[56:57], v[56:57], v[212:213] op_sel_hi:[1,0]
	v_pk_mul_f32 v[54:55], v[54:55], v[212:213] op_sel_hi:[1,0]
	v_pk_mul_f32 v[52:53], v[52:53], v[212:213] op_sel_hi:[1,0]
	v_max_f32_e32 v50, 0, v50
	v_max_f32_e32 v51, 0, v51
	global_store_dwordx4 v[62:63], v[58:61], off
	v_max_f32_e32 v54, 0, v54
	v_max_f32_e32 v55, 0, v55
	v_pk_mul_f32 v[58:59], v[50:51], v[50:51]
	v_max_f32_e32 v50, 0, v56
	v_max_f32_e32 v52, 0, v52
	v_max_f32_e32 v51, 0, v57
	v_max_f32_e32 v53, 0, v53
	v_pk_mul_f32 v[54:55], v[54:55], v[54:55]
	v_pk_mul_f32 v[56:57], v[50:51], v[50:51]
	v_pk_mul_f32 v[60:61], v[52:53], v[52:53]
	v_cvt_pk_bf16_f32 v50, v54, v55
	v_cvt_pk_bf16_f32 v51, v56, v57
	v_cvt_pk_bf16_f32 v52, v58, v59
	v_cvt_pk_bf16_f32 v53, v60, v61
	global_store_dwordx4 v[62:63], v[50:53], off offset:256
	s_nop 1
	v_add_u32_e32 v50, 0x90, v158
	v_ashrrev_i32_e32 v51, 31, v50
	v_lshlrev_b64 v[52:53], 7, v[50:51]
	v_lshl_add_u64 v[52:53], v[152:153], 0, v[52:53]
	v_lshlrev_b64 v[50:51], 14, v[50:51]
	v_pk_mul_f32 v[46:47], v[46:47], v[214:215] op_sel_hi:[1,0]
	v_pk_mul_f32 v[42:43], v[42:43], v[214:215] op_sel_hi:[1,0]
	v_pk_mul_f32 v[48:49], v[48:49], v[214:215] op_sel_hi:[1,0]
	v_pk_mul_f32 v[44:45], v[44:45], v[214:215] op_sel_hi:[1,0]
; __device__ __forceinline__ unsigned cvt_pk_bf16(float lo, float hi) { const f32x2c_t v = {lo, hi}; const bf16x2c_t b = __builtin_convertvector(v, bf16x2c_t); return __builtin_bit_cast(unsigned, b); }
;     __device__ __forceinline__ void operator()(const f32x4 (&acc)[2][2][4][2], const Unit& u, int wr, int wc, int fr, int fq) const {
;     ...
;             for (int m = 0; m < 4; ++m) { const size_t row = (size_t)(row0 + ai * HALF + m * 16);
;                 const f32x4* sp = (const f32x4*)(SS + row * 32) + 2 * fq; float s;
;                 { const f32x4 t0 = sp[0], t1 = sp[1]; s = ((t0[0] + t0[1]) + (t0[2] + t0[3])) + ((t1[0] + t1[1]) + (t1[2] + t1[3])); }
;                 s += __shfl_xor(s, 16); s += __shfl_xor(s, 32);
;                 const float rstd = 1.0f / sqrtf(s * (1.0f / DM) + NORM_EPS);
; #pragma unroll
;                 for (int bj = 0; bj < 2; ++bj) { f32x4 v0 = acc[ai][bj][m][0] * rstd, v1 = acc[ai][bj][m][1] * rstd;
; #pragma unroll
;                     for (int e = 0; e < 4; ++e) { const float a = fmaxf(v0[e], 0.f), b = fmaxf(v1[e], 0.f); v0[e] = a * a; v1[e] = b * b; }
;                     u32x4 w; w.x = cvt_pk_bf16(v0[0], v0[1]); w.y = cvt_pk_bf16(v0[2], v0[3]); w.z = cvt_pk_bf16(v1[0], v1[1]); w.w = cvt_pk_bf16(v1[2], v1[3]);
;                     *(u32x4*)(H + row * DFF + col0 + bj * HALF) = w; } }
	v_max_f32_e32 v46, 0, v46
	v_max_f32_e32 v42, 0, v42
	v_max_f32_e32 v47, 0, v47
	v_max_f32_e32 v43, 0, v43
	v_pk_mul_f32 v[46:47], v[46:47], v[46:47]
	v_pk_mul_f32 v[54:55], v[42:43], v[42:43]
	v_max_f32_e32 v42, 0, v48
	v_max_f32_e32 v44, 0, v44
	v_max_f32_e32 v43, 0, v49
	v_max_f32_e32 v45, 0, v45
	v_pk_mul_f32 v[48:49], v[42:43], v[42:43]
	v_pk_mul_f32 v[56:57], v[44:45], v[44:45]
	v_cvt_pk_bf16_f32 v42, v46, v47
	v_lshl_add_u64 v[46:47], s[92:93], 0, v[50:51]
	v_pk_mul_f32 v[34:35], v[34:35], v[214:215] op_sel_hi:[1,0]
	v_cvt_pk_bf16_f32 v43, v48, v49
	v_cvt_pk_bf16_f32 v44, v54, v55
	v_cvt_pk_bf16_f32 v45, v56, v57
	v_lshl_add_u64 v[46:47], v[46:47], 0, v[122:123]
	v_pk_mul_f32 v[40:41], v[40:41], v[214:215] op_sel_hi:[1,0]
	v_pk_mul_f32 v[38:39], v[38:39], v[214:215] op_sel_hi:[1,0]
	v_pk_mul_f32 v[36:37], v[36:37], v[214:215] op_sel_hi:[1,0]
	v_max_f32_e32 v34, 0, v34
	v_max_f32_e32 v35, 0, v35
	global_store_dwordx4 v[46:47], v[42:45], off
	v_max_f32_e32 v38, 0, v38
	v_max_f32_e32 v39, 0, v39
	v_pk_mul_f32 v[42:43], v[34:35], v[34:35]
	v_max_f32_e32 v34, 0, v40
	v_max_f32_e32 v36, 0, v36
	v_max_f32_e32 v35, 0, v41
	v_max_f32_e32 v37, 0, v37
	v_pk_mul_f32 v[38:39], v[38:39], v[38:39]
	v_pk_mul_f32 v[40:41], v[34:35], v[34:35]
	v_pk_mul_f32 v[44:45], v[36:37], v[36:37]
	v_cvt_pk_bf16_f32 v34, v38, v39
	v_cvt_pk_bf16_f32 v35, v40, v41
	v_cvt_pk_bf16_f32 v36, v42, v43
	v_cvt_pk_bf16_f32 v37, v44, v45
	global_store_dwordx4 v[46:47], v[34:37], off offset:256
	s_nop 1
	v_add_u32_e32 v34, 0xa0, v158
	v_ashrrev_i32_e32 v35, 31, v34
	v_lshlrev_b64 v[36:37], 7, v[34:35]
	v_lshl_add_u64 v[36:37], v[152:153], 0, v[36:37]
	v_lshlrev_b64 v[34:35], 14, v[34:35]
	v_pk_mul_f32 v[30:31], v[30:31], v[216:217] op_sel_hi:[1,0]
	v_pk_mul_f32 v[26:27], v[26:27], v[216:217] op_sel_hi:[1,0]
	v_pk_mul_f32 v[32:33], v[32:33], v[216:217] op_sel_hi:[1,0]
	v_pk_mul_f32 v[28:29], v[28:29], v[216:217] op_sel_hi:[1,0]
	v_max_f32_e32 v30, 0, v30
	v_max_f32_e32 v26, 0, v26
	v_max_f32_e32 v31, 0, v31
	v_max_f32_e32 v27, 0, v27
	v_pk_mul_f32 v[30:31], v[30:31], v[30:31]
	v_pk_mul_f32 v[38:39], v[26:27], v[26:27]
	v_max_f32_e32 v26, 0, v32
	v_max_f32_e32 v28, 0, v28
	v_max_f32_e32 v27, 0, v33
	v_max_f32_e32 v29, 0, v29
	v_pk_mul_f32 v[32:33], v[26:27], v[26:27]
	v_pk_mul_f32 v[40:41], v[28:29], v[28:29]
	v_cvt_pk_bf16_f32 v26, v30, v31
	v_lshl_add_u64 v[30:31], s[92:93], 0, v[34:35]
	v_pk_mul_f32 v[18:19], v[18:19], v[216:217] op_sel_hi:[1,0]
	v_cvt_pk_bf16_f32 v27, v32, v33
	v_cvt_pk_bf16_f32 v28, v38, v39
	v_cvt_pk_bf16_f32 v29, v40, v41
	v_lshl_add_u64 v[30:31], v[30:31], 0, v[122:123]
	v_pk_mul_f32 v[24:25], v[24:25], v[216:217] op_sel_hi:[1,0]
	v_pk_mul_f32 v[22:23], v[22:23], v[216:217] op_sel_hi:[1,0]
	v_pk_mul_f32 v[20:21], v[20:21], v[216:217] op_sel_hi:[1,0]
	v_max_f32_e32 v18, 0, v18
	v_max_f32_e32 v19, 0, v19
	global_store_dwordx4 v[30:31], v[26:29], off
	v_max_f32_e32 v22, 0, v22
	v_max_f32_e32 v23, 0, v23
	v_pk_mul_f32 v[26:27], v[18:19], v[18:19]
	v_max_f32_e32 v18, 0, v24
	v_max_f32_e32 v20, 0, v20
	v_max_f32_e32 v19, 0, v25
	v_max_f32_e32 v21, 0, v21
	v_pk_mul_f32 v[22:23], v[22:23], v[22:23]
	v_pk_mul_f32 v[24:25], v[18:19], v[18:19]
	v_pk_mul_f32 v[28:29], v[20:21], v[20:21]
	v_cvt_pk_bf16_f32 v18, v22, v23
	v_cvt_pk_bf16_f32 v19, v24, v25
	v_cvt_pk_bf16_f32 v20, v26, v27
	v_cvt_pk_bf16_f32 v21, v28, v29
	global_store_dwordx4 v[30:31], v[18:21], off offset:256
	s_nop 1
	v_add_u32_e32 v18, 0xb0, v158
	v_ashrrev_i32_e32 v19, 31, v18
	v_lshlrev_b64 v[20:21], 7, v[18:19]
	v_lshl_add_u64 v[20:21], v[152:153], 0, v[20:21]
	v_lshlrev_b64 v[18:19], 14, v[18:19]
	s_mov_b64 s[0:1], -1
	v_pk_mul_f32 v[14:15], v[14:15], v[218:219] op_sel_hi:[1,0]
	v_pk_mul_f32 v[10:11], v[10:11], v[218:219] op_sel_hi:[1,0]
	v_pk_mul_f32 v[16:17], v[16:17], v[218:219] op_sel_hi:[1,0]
	v_pk_mul_f32 v[12:13], v[12:13], v[218:219] op_sel_hi:[1,0]
	v_max_f32_e32 v14, 0, v14
	v_max_f32_e32 v10, 0, v10
	v_max_f32_e32 v15, 0, v15
	v_max_f32_e32 v11, 0, v11
	v_pk_mul_f32 v[14:15], v[14:15], v[14:15]
	v_pk_mul_f32 v[22:23], v[10:11], v[10:11]
	v_max_f32_e32 v10, 0, v16
	v_max_f32_e32 v12, 0, v12
	v_max_f32_e32 v11, 0, v17
	v_max_f32_e32 v13, 0, v13
	v_pk_mul_f32 v[16:17], v[10:11], v[10:11]
	v_pk_mul_f32 v[24:25], v[12:13], v[12:13]
	v_cvt_pk_bf16_f32 v10, v14, v15
	v_lshl_add_u64 v[14:15], s[92:93], 0, v[18:19]
	v_pk_mul_f32 v[2:3], v[2:3], v[218:219] op_sel_hi:[1,0]
	v_cvt_pk_bf16_f32 v11, v16, v17
	v_cvt_pk_bf16_f32 v12, v22, v23
	v_cvt_pk_bf16_f32 v13, v24, v25
	v_lshl_add_u64 v[14:15], v[14:15], 0, v[122:123]
	v_pk_mul_f32 v[8:9], v[8:9], v[218:219] op_sel_hi:[1,0]
	v_pk_mul_f32 v[6:7], v[6:7], v[218:219] op_sel_hi:[1,0]
	v_pk_mul_f32 v[4:5], v[4:5], v[218:219] op_sel_hi:[1,0]
	v_max_f32_e32 v2, 0, v2
	v_max_f32_e32 v3, 0, v3
	global_store_dwordx4 v[14:15], v[10:13], off
	v_max_f32_e32 v6, 0, v6
	v_max_f32_e32 v7, 0, v7
	v_pk_mul_f32 v[10:11], v[2:3], v[2:3]
	v_max_f32_e32 v2, 0, v8
	v_max_f32_e32 v4, 0, v4
	v_max_f32_e32 v3, 0, v9
	v_max_f32_e32 v5, 0, v5
	v_pk_mul_f32 v[6:7], v[6:7], v[6:7]
	v_pk_mul_f32 v[8:9], v[2:3], v[2:3]
	v_pk_mul_f32 v[12:13], v[4:5], v[4:5]
	v_cvt_pk_bf16_f32 v2, v6, v7
	v_cvt_pk_bf16_f32 v3, v8, v9
	v_cvt_pk_bf16_f32 v4, v10, v11
	v_cvt_pk_bf16_f32 v5, v12, v13
	s_andn2_b64 vcc, exec, s[40:41]
	global_store_dwordx4 v[14:15], v[2:5], off offset:256
	s_cbranch_vccnz .LBB0_68
	s_andn2_b64 vcc, exec, s[12:13]
	s_cbranch_vccnz .LBB0_67
	s_barrier
	s_branch .LBB0_67
